# attention younger half: first two K fragment stages of QK read in front of the preceding barrier
# speedup vs baseline: 1.0119x; 1.0012x over previous
; #define ATT_WAIT(n) asm volatile("s_waitcnt vmcnt(" #n ")" ::: "memory")
; #define ATT_BAR() do { asm volatile("s_waitcnt lgkmcnt(0)" ::: "memory"); __builtin_amdgcn_s_barrier(); asm volatile("" ::: "memory"); } while (0)
; #define ATT_ISSUE_K() attn_issue_k(F, KH + (size_t)ATT_TILE((t + 2 < nt) ? t + 2 : nt - 1) * ATT_KB, lds + b2 * ATT_KB)
; #define ATT_ISSUE_V() attn_issue_v(F, VT + (size_t)ATT_TILE((t + 2 < nt) ? t + 2 : nt - 1) * ATT_VB, lds + ATT_VBASE + b2 * ATT_VB)
; __device__ __forceinline__ void attn_unit(const Frame& F, int h, int qb, const float* qw, bool desc) {
;     ...
;         for (int t = 0; t < nt; ++t) {
;             const int tl = ATT_TILE(t), tlp = ATT_TILE(t - 1);
;             ATT_ISSUE_K(); if (t > 0) { ATT_SMPV(tlp, bp); } ATT_WAIT(8); ATT_BAR();
;             ATT_ISSUE_V(); ATT_QK(tl, b0); ATT_WAIT(7); ATT_BAR();
.LBB0_1013:
	s_lshl_b32 s89, s89, 14
	s_add_u32 s92, s42, s89
	s_addc_u32 s93, s43, 0
	s_lshl_b32 s89, s75, 14
	s_add_i32 s89, s89, 0x12000
	s_add_i32 vcc_lo, s89, s59
	s_add_i32 vcc_hi, s89, s60
	s_add_u32 s98, s92, s14
	s_addc_u32 s99, s93, s15
	s_add_u32 s100, s92, s16
	s_addc_u32 s101, s93, s17
	s_mul_i32 s89, s0, 0x6000
	v_add_u32_e32 v2, s89, v174
	v_add_u32_e32 v16, s89, v175
	v_add_u32_e32 v17, s89, v176
	v_add_u32_e32 v185, s89, v177
	ds_read_b128 v[4:7], v2
	ds_read_b128 v[8:11], v2 offset:12288
	ds_read_b128 v[12:15], v16
	ds_read_b128 v[186:189], v16 offset:12288
	ds_read_b128 v[190:193], v17
	ds_read_b128 v[194:197], v17 offset:12288
	ds_read_b128 v[198:201], v185
	ds_read_b128 v[202:205], v185 offset:12288
	s_waitcnt vmcnt(8)
	s_waitcnt lgkmcnt(0)
	s_barrier
	s_setprio 1
	s_cmp_gt_i32 s90, s70
	s_cbranch_scc1 .Lmy_attn_skipqk_b
	v_mfma_f32_32x32x16_bf16 v[98:113], v[4:7], v[114:117], 0
	v_mfma_f32_32x32x16_bf16 v[98:113], v[12:15], v[118:121], v[98:113]
	ds_read_b128 v[206:209], v2 offset:128
	ds_read_b128 v[210:213], v2 offset:12416
	ds_read_b128 v[214:217], v16 offset:128
	ds_read_b128 v[218:221], v16 offset:12416
	s_waitcnt lgkmcnt(8)
	v_mfma_f32_32x32x16_bf16 v[82:97], v[8:11], v[114:117], 0
	s_mov_b32 m0, vcc_lo
	s_nop 0
	global_load_lds_dwordx4 v164, s[98:99]
	v_mfma_f32_32x32x16_bf16 v[82:97], v[186:189], v[118:121], v[82:97]
	s_mov_b32 m0, vcc_hi
	s_nop 0
	global_load_lds_dwordx4 v164, s[100:101]
	ds_read_b128 v[4:7], v17 offset:128
	ds_read_b128 v[8:11], v17 offset:12416
	ds_read_b128 v[12:15], v185 offset:128
	ds_read_b128 v[186:189], v185 offset:12416
	s_waitcnt lgkmcnt(8)
	v_mfma_f32_32x32x16_bf16 v[98:113], v[190:193], v[122:125], v[98:113]
	v_mfma_f32_32x32x16_bf16 v[98:113], v[198:201], v[126:129], v[98:113]
	v_mfma_f32_32x32x16_bf16 v[82:97], v[194:197], v[122:125], v[82:97]
	v_mfma_f32_32x32x16_bf16 v[82:97], v[202:205], v[126:129], v[82:97]
	ds_read_b128 v[190:193], v2 offset:256
	ds_read_b128 v[194:197], v2 offset:12544
	ds_read_b128 v[198:201], v16 offset:256
	ds_read_b128 v[202:205], v16 offset:12544
	s_waitcnt lgkmcnt(8)
	v_mfma_f32_32x32x16_bf16 v[98:113], v[206:209], v[130:133], v[98:113]
	v_mfma_f32_32x32x16_bf16 v[98:113], v[214:217], v[134:137], v[98:113]
	v_mfma_f32_32x32x16_bf16 v[82:97], v[210:213], v[130:133], v[82:97]
	v_mfma_f32_32x32x16_bf16 v[82:97], v[218:221], v[134:137], v[82:97]
	ds_read_b128 v[206:209], v17 offset:256
	ds_read_b128 v[210:213], v17 offset:12544
	ds_read_b128 v[214:217], v185 offset:256
	ds_read_b128 v[218:221], v185 offset:12544
	s_waitcnt lgkmcnt(8)
	v_mfma_f32_32x32x16_bf16 v[98:113], v[4:7], v[138:141], v[98:113]
	v_mfma_f32_32x32x16_bf16 v[98:113], v[12:15], v[142:145], v[98:113]
	v_mfma_f32_32x32x16_bf16 v[82:97], v[8:11], v[138:141], v[82:97]
	v_mfma_f32_32x32x16_bf16 v[82:97], v[186:189], v[142:145], v[82:97]
	s_waitcnt lgkmcnt(4)
	v_mfma_f32_32x32x16_bf16 v[98:113], v[190:193], v[146:149], v[98:113]
	v_mfma_f32_32x32x16_bf16 v[98:113], v[198:201], v[154:157], v[98:113]
	v_mfma_f32_32x32x16_bf16 v[82:97], v[194:197], v[146:149], v[82:97]
	v_mfma_f32_32x32x16_bf16 v[82:97], v[202:205], v[154:157], v[82:97]
	s_waitcnt lgkmcnt(0)
	v_mfma_f32_32x32x16_bf16 v[98:113], v[206:209], v[150:153], v[98:113]
	v_mfma_f32_32x32x16_bf16 v[98:113], v[214:217], v[158:161], v[98:113]
	v_mfma_f32_32x32x16_bf16 v[82:97], v[210:213], v[150:153], v[82:97]
	v_mfma_f32_32x32x16_bf16 v[82:97], v[218:221], v[158:161], v[82:97]
	s_branch .LBB0_1016
